# attention tile: rolling depth-3 prefetch of K/V fragments (one LDS read or read pair per MFMA, counted lgkmcnt)
# speedup vs baseline: 1.0080x; 1.0080x over previous
; __device__ __forceinline__ float fast_exp2(float x) { return __builtin_amdgcn_exp2f(x); }
; __device__ __forceinline__ float fast_rcp(float x) { return __builtin_amdgcn_rcpf(x); }
; template <int NB, bool MASK> __device__ __forceinline__ void sb_transform(f32x16* P, float& R, int hi, int kpos0, int qpos) {
;     float T[NB][4];
; #pragma unroll
;     for (int b = 0; b < NB; ++b)
; #pragma unroll
;         for (int g = 0; g < 4; ++g) {
;             float be[4], f[4];
; #pragma unroll
;             for (int i = 0; i < 4; ++i) {
;                 const float z = fmaxf(P[b][4 * g + i], -100.f);
;                 const float e = fast_exp2(-z), rc = fast_rcp(1.f + e);
;                 be[i] = rc; f[i] = e * rc;
;                 if (MASK) { const bool ok = (kpos0 + 32 * b + 8 * g + 4 * hi + i) < qpos; be[i] = ok ? be[i] : 0.f; f[i] = ok ? f[i] : 1.f; }
;             }
.LBB0_872:
	s_lshl_b32 s87, s86, 14
	v_add_u32_e32 v2, s87, v211
	v_add_u32_e32 v172, v2, v212
	v_add_u32_e32 v174, v2, v213
	v_add_u32_e32 v175, v2, v214
	v_add_u32_e32 v176, v2, v215
	v_add_u32_e32 v177, v2, v216
	v_add_u32_e32 v178, v2, v217
	v_add_u32_e32 v179, v2, v218
	v_add_u32_e32 v180, v2, v219
	ds_read_b128 v[222:225], v172 offset:40960
	ds_read_b128 v[226:229], v174 offset:40960
	ds_read_b128 v[230:233], v175 offset:40960
	s_or_b32 s11, s10, 63
	s_cmp_ge_i32 s11, s78
	s_mov_b64 s[8:9], -1
	s_cselect_b64 s[50:51], -1, 0
	v_or_b32_e32 v2, s10, v210
	s_cmp_lt_i32 s11, s78
	s_waitcnt lgkmcnt(2)
	v_mfma_f32_32x32x16_bf16 v[84:99], v[222:225], v[100:103], v[68:83]
	ds_read_b128 v[238:241], v176 offset:40960
	s_waitcnt lgkmcnt(2)
	v_mfma_f32_32x32x16_bf16 v[84:99], v[226:229], v[104:107], v[84:99]
	ds_read_b128 v[222:225], v177 offset:40960
	s_waitcnt lgkmcnt(2)
	v_mfma_f32_32x32x16_bf16 v[84:99], v[230:233], v[108:111], v[84:99]
	ds_read_b128 v[226:229], v178 offset:40960
	s_waitcnt lgkmcnt(2)
	v_mfma_f32_32x32x16_bf16 v[84:99], v[238:241], v[112:115], v[84:99]
	ds_read_b128 v[230:233], v179 offset:40960
	s_waitcnt lgkmcnt(2)
	v_mfma_f32_32x32x16_bf16 v[84:99], v[222:225], v[116:119], v[84:99]
	ds_read_b128 v[238:241], v180 offset:40960
	s_waitcnt lgkmcnt(2)
	v_mfma_f32_32x32x16_bf16 v[84:99], v[226:229], v[120:123], v[84:99]
	s_waitcnt lgkmcnt(1)
	v_mfma_f32_32x32x16_bf16 v[84:99], v[230:233], v[124:127], v[84:99]
	s_waitcnt lgkmcnt(0)
	v_mfma_f32_32x32x16_bf16 v[84:99], v[238:241], v[128:131], v[84:99]
	s_nop 11
	v_max_f32_e64 v227, -v84, -v84
	v_max_f32_e64 v226, -v85, -v85
	v_max_f32_e64 v225, -v86, -v86
	v_max_f32_e64 v224, -v87, -v87
	v_max_f32_e64 v223, -v88, -v88
	v_max_f32_e64 v222, -v89, -v89
	v_max_f32_e64 v221, -v90, -v90
	v_max_f32_e64 v189, -v91, -v91
	v_max_f32_e64 v188, -v92, -v92
	v_max_f32_e64 v187, -v93, -v93
	v_max_f32_e64 v186, -v94, -v94
	v_max_f32_e64 v185, -v95, -v95
	v_max_f32_e64 v183, -v96, -v96
	v_max_f32_e64 v184, -v97, -v97
	v_max_f32_e64 v182, -v98, -v98
	v_max_f32_e64 v181, -v99, -v99
	s_cbranch_scc1 .LBB0_874
	v_min_f32_e32 v84, 0x42c80000, v227
	v_exp_f32_e32 v84, v84
	v_min_f32_e32 v85, 0x42c80000, v226
	v_exp_f32_e32 v85, v85
	v_or_b32_e32 v87, 32, v2
	v_add_f32_e32 v86, 1.0, v84
	v_rcp_f32_e32 v86, v86
	v_add_f32_e32 v88, 1.0, v85
	v_rcp_f32_e32 v88, v88
	v_min_f32_e32 v90, 0x42c80000, v224
	v_mul_f32_e32 v89, v84, v86
	v_cmp_lt_i32_e32 vcc, v87, v168
	v_exp_f32_e32 v90, v90
	v_mul_f32_e32 v87, v85, v88
	v_cndmask_b32_e32 v84, 0, v86, vcc
	v_cndmask_b32_e32 v86, 1.0, v89, vcc
	v_or_b32_e32 v89, 33, v2
	v_mov_b32_e32 v85, s45
	v_cmp_lt_i32_e32 vcc, v89, v168
	v_min_f32_e32 v91, 0x42c80000, v223
	v_exp_f32_e32 v93, v91
	v_cndmask_b32_e32 v85, v85, v88, vcc
	v_min_f32_e32 v88, 0x42c80000, v225
	v_exp_f32_e32 v92, v88
	v_add_f32_e32 v88, 1.0, v90
	v_rcp_f32_e32 v89, v88
	v_min_f32_e32 v91, 0x42c80000, v222
	v_exp_f32_e32 v91, v91
	v_cndmask_b32_e32 v88, 1.0, v87, vcc
	v_add_f32_e32 v87, 1.0, v92
	v_rcp_f32_e32 v96, v87
	v_mul_f32_e32 v87, v90, v89
	v_or_b32_e32 v90, 35, v2
	v_cmp_lt_i32_e32 vcc, v90, v168
	v_add_f32_e32 v90, 1.0, v91
	v_rcp_f32_e32 v95, v90
	v_min_f32_e32 v90, 0x42c80000, v221
	v_exp_f32_e32 v90, v90
	v_cndmask_b32_e32 v94, 1.0, v87, vcc
	v_add_f32_e32 v87, 1.0, v93
	v_rcp_f32_e32 v97, v87
	v_add_f32_e32 v98, 1.0, v90
	v_rcp_f32_e32 v99, v98
	v_min_f32_e32 v98, 0x42c80000, v189
	v_exp_f32_e32 v98, v98
	v_mul_f32_e32 v87, v91, v95
	v_or_b32_e32 v91, 41, v2
	v_cmp_lt_i32_e64 s[8:9], v91, v168
	v_min_f32_e32 v91, 0x42c80000, v188
	v_exp_f32_e32 v91, v91
	v_cndmask_b32_e64 v173, 1.0, v87, s[8:9]
	v_mul_f32_e32 v87, v90, v99
	v_add_f32_e32 v90, 1.0, v98
	v_rcp_f32_e32 v231, v90
	v_or_b32_e32 v90, 42, v2
	v_cmp_lt_i32_e64 s[10:11], v90, v168
	v_or_b32_e32 v90, 43, v2
	v_cmp_lt_i32_e64 s[12:13], v90, v168
	v_cndmask_b32_e64 v248, 1.0, v87, s[10:11]
	v_mul_f32_e32 v87, v98, v231
	v_cndmask_b32_e64 v249, 1.0, v87, s[12:13]
	v_min_f32_e32 v87, 0x42c80000, v187
	v_add_f32_e32 v90, 1.0, v91
	v_exp_f32_e32 v87, v87
	v_rcp_f32_e32 v242, v90
	v_or_b32_e32 v90, 48, v2
	v_cmp_lt_i32_e64 s[14:15], v90, v168
	v_add_f32_e32 v98, 1.0, v87
	v_mul_f32_e32 v91, v91, v242
	v_min_f32_e32 v90, 0x42c80000, v185
	v_min_f32_e32 v230, 0x42c80000, v184
	v_rcp_f32_e32 v243, v98
	v_cndmask_b32_e64 v98, 1.0, v91, s[14:15]
	v_exp_f32_e32 v91, v90
	v_exp_f32_e32 v232, v230
	v_min_f32_e32 v90, 0x42c80000, v186
	v_or_b32_e32 v229, 51, v2
	v_exp_f32_e32 v90, v90
	v_add_f32_e32 v228, 1.0, v91
	v_cmp_lt_i32_e64 s[20:21], v229, v168
	v_add_f32_e32 v229, 1.0, v232
	v_rcp_f32_e32 v244, v228
	v_rcp_f32_e32 v245, v229
	v_min_f32_e32 v229, 0x42c80000, v182
	v_or_b32_e32 v170, 49, v2
	v_exp_f32_e32 v233, v229
; __device__ __forceinline__ float fast_exp2(float x) { return __builtin_amdgcn_exp2f(x); }
; __device__ __forceinline__ float fast_rcp(float x) { return __builtin_amdgcn_rcpf(x); }
; template <int NB, bool MASK> __device__ __forceinline__ void sb_transform(f32x16* P, float& R, int hi, int kpos0, int qpos) {
;     float T[NB][4];
; #pragma unroll
;     for (int b = 0; b < NB; ++b)
; #pragma unroll
;         for (int g = 0; g < 4; ++g) {
;             float be[4], f[4];
; #pragma unroll
;             for (int i = 0; i < 4; ++i) {
;                 const float z = fmaxf(P[b][4 * g + i], -100.f);
;                 const float e = fast_exp2(-z), rc = fast_rcp(1.f + e);
;                 be[i] = rc; f[i] = e * rc;
;                 if (MASK) { const bool ok = (kpos0 + 32 * b + 8 * g + 4 * hi + i) < qpos; be[i] = ok ? be[i] : 0.f; f[i] = ok ? f[i] : 1.f; }
;             }
;             const float e2 = f[3], e1 = f[2] * f[3], e0 = f[1] * e1;
;             T[b][g] = f[0] * e0;
;             P[b][4 * g + 0] = be[0] * e0; P[b][4 * g + 1] = be[1] * e1; P[b][4 * g + 2] = be[2] * e2; P[b][4 * g + 3] = be[3];
;         }
;     float E = R;
; #pragma unroll
;     for (int b = NB - 1; b >= 0; --b)
; #pragma unroll
;         for (int g = 3; g >= 0; --g) {
;             const float To = __shfl_xor(T[b][g], 32);
;             const float Eg = hi ? E : E * To;
; #pragma unroll
;             for (int i = 0; i < 4; ++i) P[b][4 * g + i] *= Eg;
;             E = E * T[b][g] * To;
;         }
;     R = E;
; }
	v_mul_f32_e32 v87, v87, v243
	v_cmp_lt_i32_e64 s[16:17], v170, v168
	v_pk_mul_f32 v[92:93], v[92:93], v[96:97]
	v_add_f32_e32 v234, 1.0, v233
	v_cndmask_b32_e64 v170, 1.0, v87, s[16:17]
	v_add_f32_e32 v87, 1.0, v90
	v_rcp_f32_e32 v228, v87
	v_mul_f32_e32 v87, v91, v244
	v_min_f32_e32 v91, 0x42c80000, v183
	v_exp_f32_e32 v91, v91
	v_rcp_f32_e32 v246, v234
	v_min_f32_e32 v234, 0x42c80000, v181
	v_exp_f32_e32 v234, v234
	v_cndmask_b32_e64 v230, 1.0, v87, s[20:21]
	v_add_f32_e32 v87, 1.0, v91
	v_rcp_f32_e32 v229, v87
	v_mul_f32_e32 v87, v232, v245
	v_or_b32_e32 v232, 57, v2
	v_cmp_lt_i32_e64 s[26:27], v232, v168
	v_add_f32_e32 v232, 1.0, v234
	v_rcp_f32_e32 v250, v232
	v_or_b32_e32 v232, 58, v2
	v_cndmask_b32_e64 v247, 1.0, v87, s[26:27]
	v_mul_f32_e32 v87, v233, v246
	v_cmp_lt_i32_e64 s[22:23], v232, v168
	v_or_b32_e32 v232, 59, v2
	v_cmp_lt_i32_e64 s[18:19], v232, v168
	v_cndmask_b32_e64 v251, 1.0, v87, s[22:23]
	v_mul_f32_e32 v87, v234, v250
	v_cndmask_b32_e64 v252, 1.0, v87, s[18:19]
	v_xor_b32_e32 v87, 32, v191
	v_add_u32_e32 v232, 64, v192
	v_cmp_lt_i32_e64 s[28:29], v87, v232
	v_or_b32_e32 v232, 50, v2
	v_pk_mul_f32 v[90:91], v[90:91], v[228:229]
	v_cndmask_b32_e64 v87, v191, v87, s[28:29]
	v_lshlrev_b32_e32 v253, 2, v87
	v_or_b32_e32 v87, 56, v2
	v_cmp_lt_i32_e64 s[28:29], v87, v1
	v_or_b32_e32 v87, 34, v2
	v_cmp_lt_i32_e64 s[30:31], v232, v168
	v_cmp_lt_i32_e64 s[34:35], v87, v168
	v_cndmask_b32_e64 v233, 1.0, v91, s[28:29]
	v_cndmask_b32_e64 v232, 1.0, v90, s[30:31]
	v_cndmask_b32_e64 v90, 0, v96, s[34:35]
	v_or_b32_e32 v91, 40, v2
	v_mov_b32_e32 v87, s45
	v_mul_f32_e32 v234, v94, v90
	v_mov_b32_e32 v90, s45
	v_cndmask_b32_e32 v235, v87, v89, vcc
	v_cmp_lt_i32_e32 vcc, v91, v1
	v_cndmask_b32_e64 v90, v90, v99, s[10:11]
	v_mul_f32_e32 v91, v251, v252
	v_cndmask_b32_e64 v241, v87, v231, s[12:13]
	v_mul_f32_e32 v240, v249, v90
	v_mov_b32_e32 v90, s45
	v_mul_f32_e32 v231, v247, v91
	v_cndmask_b32_e64 v236, 1.0, v92, s[34:35]
	v_cndmask_b32_e64 v96, v90, v242, s[14:15]
	v_cndmask_b32_e64 v90, 0, v228, s[30:31]
	v_cndmask_b32_e64 v92, 0, v229, s[28:29]
	v_pk_mul_f32 v[228:229], v[232:233], v[230:231]
	v_mov_b32_e32 v99, v229
	v_mov_b32_e32 v255, v229
	s_nop 1
	v_permlane32_swap_b32_e32 v99, v255
	v_cndmask_b32_e64 v99, v99, v255, s[6:7]
	v_pk_mul_f32 v[232:233], v[170:171], v[228:229]
	v_cndmask_b32_e32 v237, 1.0, v93, vcc
	v_cndmask_b32_e32 v238, 0, v97, vcc
	v_cndmask_b32_e64 v97, v87, v243, s[16:17]
	v_cndmask_b32_e64 v243, v87, v244, s[20:21]
	v_cndmask_b32_e64 v93, v87, v245, s[26:27]
	s_waitcnt lgkmcnt(0)
	v_pk_mul_f32 v[244:245], v[98:99], v[232:233]
	v_mov_b32_e32 v89, v244
	v_mov_b32_e32 v255, v244
	s_nop 1
	v_permlane32_swap_b32_e32 v89, v255
	v_cndmask_b32_e64 v89, v89, v255, s[6:7]
	v_cndmask_b32_e64 v239, v87, v95, s[8:9]
	v_mul_f32_e32 v242, v230, v90
	v_mov_b32_e32 v90, s45
	v_cndmask_b32_e64 v247, v87, v250, s[18:19]
	v_mul_f32_e32 v87, v171, v99
	v_mul_f32_e32 v229, v248, v249
	v_cndmask_b32_e64 v90, v90, v246, s[22:23]
	v_cndmask_b32_e64 v98, v171, v87, s[6:7]
	s_waitcnt lgkmcnt(0)
	v_mul_f32_e32 v87, v245, v89
	v_mul_f32_e32 v95, v173, v229
	v_mul_f32_e32 v246, v252, v90
	v_cndmask_b32_e64 v170, v245, v87, s[6:7]
	v_mul_f32_e32 v87, v244, v245
	v_mov_b32_e32 v90, v231
	v_pk_mul_f32 v[230:231], v[236:237], v[94:95]
	v_mul_f32_e32 v89, v87, v89
	v_mov_b32_e32 v87, v231
	v_mov_b32_e32 v255, v231
	s_nop 1
	v_permlane32_swap_b32_e32 v87, v255
	v_cndmask_b32_e64 v87, v87, v255, s[6:7]
	v_mov_b32_e32 v233, v228
	v_pk_mul_f32 v[96:97], v[232:233], v[96:97]
	v_pk_mul_f32 v[232:233], v[88:89], v[230:231]
	v_mov_b32_e32 v228, v95
	v_pk_mul_f32 v[90:91], v[90:91], v[92:93]
	v_pk_mul_f32 v[94:95], v[228:229], v[238:239]
	s_waitcnt lgkmcnt(0)
	v_pk_mul_f32 v[228:229], v[86:87], v[232:233]
	v_pk_mul_f32 v[90:91], v[90:91], v[98:99] op_sel_hi:[1,0]
	v_pk_mul_f32 v[92:93], v[246:247], v[98:99] op_sel_hi:[1,0]
	v_pk_mul_f32 v[96:97], v[96:97], v[170:171] op_sel_hi:[1,0]
	v_pk_mul_f32 v[98:99], v[242:243], v[170:171] op_sel_hi:[1,0]
	v_mov_b32_e32 v170, v228
	v_mov_b32_e32 v255, v228
	s_nop 1
	v_permlane32_swap_b32_e32 v170, v255
	v_cndmask_b32_e64 v170, v170, v255, s[6:7]
	v_mul_f32_e32 v86, v89, v87
	v_cndmask_b32_e64 v86, v89, v86, s[6:7]
	v_pk_mul_f32 v[88:89], v[94:95], v[86:87] op_sel_hi:[1,0]
	v_mov_b32_e32 v233, v230
	s_waitcnt lgkmcnt(0)
	v_mul_f32_e32 v94, v229, v170
	v_cndmask_b32_e64 v94, v229, v94, s[6:7]
	v_pk_mul_f32 v[84:85], v[232:233], v[84:85]
	v_mul_f32_e32 v173, v228, v229
	v_pk_mul_f32 v[86:87], v[240:241], v[86:87] op_sel_hi:[1,0]
	v_pk_mul_f32 v[84:85], v[84:85], v[94:95] op_sel_hi:[1,0]
	v_pk_mul_f32 v[94:95], v[234:235], v[94:95] op_sel_hi:[1,0]
	v_mul_f32_e32 v173, v173, v170
	s_mov_b64 s[8:9], 0

; #define SBAR() __builtin_amdgcn_sched_barrier(0)
; template <int D0, int KS0> __device__ __forceinline__ void pv_one(f32x16& od, int vb, const bf16x8* pa) {
;     const s16x4 l0 = tr_read<v_rd_off(D0, KS0, 0)>(vb), h0 = tr_read<v_rd_off(D0, KS0, 1)>(vb), l1 = tr_read<v_rd_off(D0, KS0 + 1, 0)>(vb), h1 = tr_read<v_rd_off(D0, KS0 + 1, 1)>(vb);
;     asm volatile("s_waitcnt lgkmcnt(0)" ::: "memory"); SBAR();
;     od = __builtin_amdgcn_mfma_f32_32x32x16_bf16(pa[0], PKV(l0, h0), od, 0, 0, 0);
;     od = __builtin_amdgcn_mfma_f32_32x32x16_bf16(pa[1], PKV(l1, h1), od, 0, 0, 0);
; }
; template <int KS0> __device__ __forceinline__ void pv_blk(f32x16* o, int vb, const bf16x8* pa) {
;     pv_one<0, KS0>(o[0], vb, pa); pv_one<1, KS0>(o[1], vb, pa); pv_one<2, KS0>(o[2], vb, pa); pv_one<3, KS0>(o[3], vb, pa);
; }
; template <int MODE> ...
;     ...
;             ATT_BLOCK(1);
;             ATT_BLOCK(0);
.LBB0_876:
	v_cvt_pk_bf16_f32 v182, v84, v85
	v_cvt_pk_bf16_f32 v183, v94, v95
	v_cvt_pk_bf16_f32 v184, v88, v89
	v_cvt_pk_bf16_f32 v185, v86, v87
	v_cvt_pk_bf16_f32 v234, v96, v97
	v_cvt_pk_bf16_f32 v235, v98, v99
	v_cvt_pk_bf16_f32 v236, v90, v91
	v_cvt_pk_bf16_f32 v237, v92, v93
	s_nop 0
	v_permlane32_swap_b32_e32 v182, v184
	v_permlane32_swap_b32_e32 v183, v185
	v_permlane32_swap_b32_e32 v234, v236
	v_permlane32_swap_b32_e32 v235, v237
	v_add_u32_e32 v170, s87, v220
	ds_read_b64_tr_b16 v[84:85], v170 offset:8192
	ds_read_b64_tr_b16 v[86:87], v170 offset:10240
	ds_read_b64_tr_b16 v[88:89], v170 offset:12288
	ds_read_b64_tr_b16 v[90:91], v170 offset:14336
	ds_read_b64_tr_b16 v[92:93], v170 offset:8704
	ds_read_b64_tr_b16 v[94:95], v170 offset:10752
	s_waitcnt lgkmcnt(4)
	v_mfma_f32_32x32x16_bf16 v[52:67], v[182:185], v[84:87], v[52:67]
	ds_read_b64_tr_b16 v[96:97], v170 offset:12800
	ds_read_b64_tr_b16 v[98:99], v170 offset:14848
	s_waitcnt lgkmcnt(4)
	v_mfma_f32_32x32x16_bf16 v[52:67], v[234:237], v[88:91], v[52:67]
	ds_read_b64_tr_b16 v[84:85], v170 offset:9216
	ds_read_b64_tr_b16 v[86:87], v170 offset:11264
	s_waitcnt lgkmcnt(4)
	v_mfma_f32_32x32x16_bf16 v[36:51], v[182:185], v[92:95], v[36:51]
	ds_read_b64_tr_b16 v[88:89], v170 offset:13312
	ds_read_b64_tr_b16 v[90:91], v170 offset:15360
	s_waitcnt lgkmcnt(4)
	v_mfma_f32_32x32x16_bf16 v[36:51], v[234:237], v[96:99], v[36:51]
	ds_read_b64_tr_b16 v[92:93], v170 offset:9728
	ds_read_b64_tr_b16 v[94:95], v170 offset:11776
	s_waitcnt lgkmcnt(4)
	v_mfma_f32_32x32x16_bf16 v[20:35], v[182:185], v[84:87], v[20:35]
	ds_read_b64_tr_b16 v[96:97], v170 offset:13824
	ds_read_b64_tr_b16 v[98:99], v170 offset:15872
	s_waitcnt lgkmcnt(4)
	v_mfma_f32_32x32x16_bf16 v[20:35], v[234:237], v[88:91], v[20:35]
	s_waitcnt lgkmcnt(2)
	v_mfma_f32_32x32x16_bf16 v[4:19], v[182:185], v[92:95], v[4:19]
	s_waitcnt lgkmcnt(0)
	v_mfma_f32_32x32x16_bf16 v[4:19], v[234:237], v[96:99], v[4:19]
	ds_read_b128 v[222:225], v172 offset:32768
	ds_read_b128 v[226:229], v174 offset:32768
	ds_read_b128 v[230:233], v175 offset:32768
	s_mov_b64 s[8:9], -1
	s_andn2_b64 vcc, exec, s[50:51]
	s_waitcnt lgkmcnt(2)
	v_mfma_f32_32x32x16_bf16 v[84:99], v[222:225], v[100:103], v[68:83]
	ds_read_b128 v[238:241], v176 offset:32768
	s_waitcnt lgkmcnt(2)
	v_mfma_f32_32x32x16_bf16 v[84:99], v[226:229], v[104:107], v[84:99]
	ds_read_b128 v[222:225], v177 offset:32768
	s_waitcnt lgkmcnt(2)
	v_mfma_f32_32x32x16_bf16 v[84:99], v[230:233], v[108:111], v[84:99]
	ds_read_b128 v[226:229], v178 offset:32768
	s_waitcnt lgkmcnt(2)
	v_mfma_f32_32x32x16_bf16 v[84:99], v[238:241], v[112:115], v[84:99]
	ds_read_b128 v[230:233], v179 offset:32768
	s_waitcnt lgkmcnt(2)
	v_mfma_f32_32x32x16_bf16 v[84:99], v[222:225], v[116:119], v[84:99]
	ds_read_b128 v[238:241], v180 offset:32768
	s_waitcnt lgkmcnt(2)
	v_mfma_f32_32x32x16_bf16 v[84:99], v[226:229], v[120:123], v[84:99]
	s_waitcnt lgkmcnt(1)
	v_mfma_f32_32x32x16_bf16 v[84:99], v[230:233], v[124:127], v[84:99]
	s_waitcnt lgkmcnt(0)
	v_mfma_f32_32x32x16_bf16 v[84:99], v[238:241], v[128:131], v[84:99]
	s_nop 11
	v_max_f32_e64 v232, -v84, -v84
	v_max_f32_e64 v231, -v85, -v85
	v_max_f32_e64 v230, -v86, -v86
	v_max_f32_e64 v229, -v87, -v87
	v_max_f32_e64 v228, -v88, -v88
	v_max_f32_e64 v227, -v89, -v89
	v_max_f32_e64 v226, -v90, -v90
	v_max_f32_e64 v225, -v91, -v91
	v_max_f32_e64 v224, -v92, -v92
	v_max_f32_e64 v223, -v93, -v93
	v_max_f32_e64 v222, -v94, -v94
	v_max_f32_e64 v221, -v95, -v95
	v_max_f32_e64 v94, -v96, -v96
	v_max_f32_e64 v95, -v97, -v97
	v_max_f32_e64 v93, -v98, -v98
	v_max_f32_e64 v92, -v99, -v99
	s_cbranch_vccnz .LBB0_878
	v_min_f32_e32 v84, 0x42c80000, v232
	v_exp_f32_e32 v84, v84
	v_min_f32_e32 v85, 0x42c80000, v231
	v_exp_f32_e32 v85, v85
	v_min_f32_e32 v91, 0x42c80000, v228
	v_add_f32_e32 v86, 1.0, v84
	v_rcp_f32_e32 v86, v86
	v_add_f32_e32 v87, 1.0, v85
	v_exp_f32_e32 v97, v91
	v_min_f32_e32 v91, 0x42c80000, v227
	v_rcp_f32_e32 v87, v87
	v_exp_f32_e32 v91, v91
	v_min_f32_e32 v90, 0x42c80000, v229
	v_exp_f32_e32 v90, v90
	v_mul_f32_e32 v88, v84, v86
	v_cmp_lt_i32_e32 vcc, v2, v168
	v_or_b32_e32 v89, 1, v2
	v_add_f32_e32 v99, 1.0, v91
	v_cndmask_b32_e32 v84, 0, v86, vcc
	v_cndmask_b32_e32 v86, 1.0, v88, vcc
	v_mul_f32_e32 v88, v85, v87
	v_mov_b32_e32 v85, s45
	v_cmp_lt_i32_e32 vcc, v89, v168
	v_rcp_f32_e32 v171, v99
	v_min_f32_e32 v99, 0x42c80000, v226
	v_cndmask_b32_e32 v85, v85, v87, vcc
	v_min_f32_e32 v87, 0x42c80000, v230
	v_exp_f32_e32 v96, v87
	v_add_f32_e32 v87, 1.0, v90
	v_exp_f32_e32 v172, v99
	v_rcp_f32_e32 v89, v87
	v_add_f32_e32 v87, 1.0, v96
	v_rcp_f32_e32 v98, v87
	v_add_f32_e32 v174, 1.0, v172
	v_mul_f32_e32 v87, v90, v89
	v_or_b32_e32 v90, 3, v2
	v_rcp_f32_e32 v175, v174
	v_min_f32_e32 v174, 0x42c80000, v225
	v_cndmask_b32_e32 v88, 1.0, v88, vcc
	v_cmp_lt_i32_e32 vcc, v90, v168
	v_exp_f32_e32 v174, v174
	v_min_f32_e32 v180, 0x42c80000, v95
	v_cndmask_b32_e32 v90, 1.0, v87, vcc
	v_add_f32_e32 v87, 1.0, v97
	v_rcp_f32_e32 v99, v87
	v_mul_f32_e32 v87, v91, v171
	v_or_b32_e32 v91, 9, v2
	v_cmp_lt_i32_e64 s[8:9], v91, v168
	v_exp_f32_e32 v182, v180
	v_or_b32_e32 v179, 19, v2
	v_cndmask_b32_e64 v91, 1.0, v87, s[8:9]
	v_mul_f32_e32 v87, v172, v175
	v_add_f32_e32 v172, 1.0, v174
	v_rcp_f32_e32 v181, v172
	v_or_b32_e32 v172, 10, v2
	v_cmp_lt_i32_e64 s[10:11], v172, v168
	v_or_b32_e32 v172, 11, v2
	v_cmp_lt_i32_e64 s[12:13], v172, v168
	v_cndmask_b32_e64 v233, 1.0, v87, s[10:11]
	v_mul_f32_e32 v87, v174, v181
; __device__ __forceinline__ float fast_exp2(float x) { return __builtin_amdgcn_exp2f(x); }
; __device__ __forceinline__ float fast_rcp(float x) { return __builtin_amdgcn_rcpf(x); }
; template <int NB, bool MASK> __device__ __forceinline__ void sb_transform(f32x16* P, float& R, int hi, int kpos0, int qpos) {
;     float T[NB][4];
; #pragma unroll
;     for (int b = 0; b < NB; ++b)
; #pragma unroll
;         for (int g = 0; g < 4; ++g) {
;             float be[4], f[4];
; #pragma unroll
;             for (int i = 0; i < 4; ++i) {
;                 const float z = fmaxf(P[b][4 * g + i], -100.f);
;                 const float e = fast_exp2(-z), rc = fast_rcp(1.f + e);
;                 be[i] = rc; f[i] = e * rc;
;                 if (MASK) { const bool ok = (kpos0 + 32 * b + 8 * g + 4 * hi + i) < qpos; be[i] = ok ? be[i] : 0.f; f[i] = ok ? f[i] : 1.f; }
;             }
;             const float e2 = f[3], e1 = f[2] * f[3], e0 = f[1] * e1;
;             T[b][g] = f[0] * e0;
;             P[b][4 * g + 0] = be[0] * e0; P[b][4 * g + 1] = be[1] * e1; P[b][4 * g + 2] = be[2] * e2; P[b][4 * g + 3] = be[3];
;         }
;     float E = R;
; #pragma unroll
;     for (int b = NB - 1; b >= 0; --b)
; #pragma unroll
;         for (int g = 3; g >= 0; --g) {
;             const float To = __shfl_xor(T[b][g], 32);
;             const float Eg = hi ? E : E * To;
; #pragma unroll
;             for (int i = 0; i < 4; ++i) P[b][4 * g + i] *= Eg;
;             E = E * T[b][g] * To;
;         }
;     R = E;
; }
	v_min_f32_e32 v174, 0x42c80000, v224
	v_exp_f32_e32 v174, v174
	v_cndmask_b32_e64 v242, 1.0, v87, s[12:13]
	v_min_f32_e32 v87, 0x42c80000, v223
	v_exp_f32_e32 v87, v87
	v_add_f32_e32 v172, 1.0, v174
	v_rcp_f32_e32 v184, v172
	v_or_b32_e32 v172, 16, v2
	v_cmp_lt_i32_e64 s[14:15], v172, v168
	v_min_f32_e32 v172, 0x42c80000, v221
	v_exp_f32_e32 v177, v172
	v_add_f32_e32 v176, 1.0, v87
	v_rcp_f32_e32 v185, v176
	v_min_f32_e32 v176, 0x42c80000, v222
	v_exp_f32_e32 v176, v176
	v_add_f32_e32 v178, 1.0, v177
	v_cmp_lt_i32_e64 s[20:21], v179, v168
	v_add_f32_e32 v179, 1.0, v182
	v_rcp_f32_e32 v186, v178
	v_rcp_f32_e32 v234, v179
	v_min_f32_e32 v179, 0x42c80000, v93
	v_or_b32_e32 v172, 17, v2
	v_exp_f32_e32 v183, v179
	v_mul_f32_e32 v87, v87, v185
	v_cmp_lt_i32_e64 s[16:17], v172, v168
	v_mul_f32_e32 v174, v174, v184
	v_add_f32_e32 v187, 1.0, v183
	v_cndmask_b32_e64 v172, 1.0, v87, s[16:17]
	v_add_f32_e32 v87, 1.0, v176
	v_rcp_f32_e32 v178, v87
	v_mul_f32_e32 v87, v177, v186
	v_min_f32_e32 v177, 0x42c80000, v94
	v_exp_f32_e32 v177, v177
	v_rcp_f32_e32 v238, v187
	v_min_f32_e32 v187, 0x42c80000, v92
	v_exp_f32_e32 v187, v187
	v_cndmask_b32_e64 v180, 1.0, v87, s[20:21]
	v_add_f32_e32 v87, 1.0, v177
	v_rcp_f32_e32 v179, v87
	v_mul_f32_e32 v87, v182, v234
	v_or_b32_e32 v182, 25, v2
	v_cmp_lt_i32_e64 s[26:27], v182, v168
	v_add_f32_e32 v182, 1.0, v187
	v_rcp_f32_e32 v240, v182
	v_or_b32_e32 v182, 26, v2
	v_cndmask_b32_e64 v236, 1.0, v87, s[26:27]
	v_mul_f32_e32 v87, v183, v238
	v_cmp_lt_i32_e64 s[22:23], v182, v168
	v_or_b32_e32 v182, 27, v2
	v_cmp_lt_i32_e64 s[18:19], v182, v168
	v_cndmask_b32_e64 v235, 1.0, v87, s[22:23]
	v_mul_f32_e32 v87, v187, v240
	v_cndmask_b32_e64 v243, 1.0, v87, s[18:19]
	v_xor_b32_e32 v87, 32, v191
	v_add_u32_e32 v182, 64, v192
	v_cmp_lt_i32_e64 s[28:29], v87, v182
	v_or_b32_e32 v182, 18, v2
	v_cmp_lt_i32_e64 s[30:31], v182, v168
	v_cndmask_b32_e64 v87, v191, v87, s[28:29]
	v_lshlrev_b32_e32 v244, 2, v87
	v_or_b32_e32 v87, 24, v2
	v_or_b32_e32 v182, 8, v2
	v_or_b32_e32 v2, 2, v2
	v_pk_mul_f32 v[176:177], v[176:177], v[178:179]
	v_cmp_lt_i32_e64 s[28:29], v87, v1
	v_cmp_lt_i32_e64 s[34:35], v2, v168
	v_mov_b32_e32 v87, s45
	v_mul_f32_e32 v235, v235, v243
	v_cndmask_b32_e64 v177, 1.0, v177, s[28:29]
	v_cndmask_b32_e64 v176, 1.0, v176, s[30:31]
	v_cndmask_b32_e64 v2, 0, v98, s[34:35]
	v_cndmask_b32_e64 v183, v87, v181, s[12:13]
	v_mul_f32_e32 v181, v236, v235
	v_mul_f32_e32 v188, v90, v2
	v_mov_b32_e32 v2, s45
	v_pk_mul_f32 v[236:237], v[176:177], v[180:181]
	v_cndmask_b32_e64 v2, v2, v175, s[10:11]
	v_mov_b32_e32 v175, v237
	v_mov_b32_e32 v255, v237
	s_nop 1
	v_permlane32_swap_b32_e32 v175, v255
	v_cndmask_b32_e64 v175, v175, v255, s[6:7]
	v_cndmask_b32_e32 v189, v87, v89, vcc
	v_cmp_lt_i32_e32 vcc, v182, v1
	v_mul_f32_e32 v182, v242, v2
	v_mov_b32_e32 v2, s45
	v_cndmask_b32_e64 v184, v2, v184, s[14:15]
	v_cndmask_b32_e64 v2, 0, v178, s[30:31]
	v_cndmask_b32_e64 v187, v87, v186, s[20:21]
	v_mul_f32_e32 v186, v180, v2
	v_mov_b32_e32 v2, s45
	v_cndmask_b32_e64 v174, 1.0, v174, s[14:15]
	v_cndmask_b32_e64 v2, v2, v238, s[22:23]
	v_pk_mul_f32 v[238:239], v[172:173], v[236:237]
	v_cndmask_b32_e64 v185, v87, v185, s[16:17]
	s_waitcnt lgkmcnt(0)
	v_pk_mul_f32 v[176:177], v[174:175], v[238:239]
	v_mov_b32_e32 v89, v176
	v_mov_b32_e32 v255, v176
	s_nop 1
	v_permlane32_swap_b32_e32 v89, v255
	v_cndmask_b32_e64 v89, v89, v255, s[6:7]
	v_cndmask_b32_e64 v178, 0, v179, s[28:29]
	v_cndmask_b32_e64 v179, v87, v234, s[26:27]
	v_mov_b32_e32 v234, v181
	v_mov_b32_e32 v239, v236
	v_pk_mul_f32 v[96:97], v[96:97], v[98:99]
	v_cndmask_b32_e64 v241, v87, v240, s[18:19]
	v_mul_f32_e32 v240, v243, v2
	v_mul_f32_e32 v2, v173, v175
	v_pk_mul_f32 v[174:175], v[234:235], v[178:179]
	v_pk_mul_f32 v[178:179], v[238:239], v[184:185]
	v_mul_f32_e32 v185, v233, v242
	v_cndmask_b32_e32 v97, 1.0, v97, vcc
	v_cndmask_b32_e64 v96, 1.0, v96, s[34:35]
	v_cndmask_b32_e32 v98, 0, v99, vcc
	v_cndmask_b32_e64 v99, v87, v171, s[8:9]
	s_waitcnt lgkmcnt(0)
	v_mul_f32_e32 v87, v177, v89
	v_mul_f32_e32 v91, v91, v185
	v_cndmask_b32_e64 v172, v177, v87, s[6:7]
	v_mul_f32_e32 v87, v176, v177
	v_pk_mul_f32 v[96:97], v[96:97], v[90:91]
	v_mul_f32_e32 v89, v87, v89
	v_mov_b32_e32 v87, v97
	v_mov_b32_e32 v255, v97
	s_nop 1
	v_permlane32_swap_b32_e32 v87, v255
	v_cndmask_b32_e64 v87, v87, v255, s[6:7]
	v_pk_mul_f32 v[180:181], v[186:187], v[172:173] op_sel_hi:[1,0]
	v_pk_mul_f32 v[186:187], v[88:89], v[96:97]
	v_mov_b32_e32 v184, v91
	v_pk_mul_f32 v[90:91], v[184:185], v[98:99]
	s_waitcnt lgkmcnt(0)
	v_pk_mul_f32 v[98:99], v[86:87], v[186:187]
	v_mov_b32_e32 v86, v98
	v_mov_b32_e32 v255, v98
	s_nop 1
	v_permlane32_swap_b32_e32 v86, v255
	v_cndmask_b32_e64 v86, v86, v255, s[6:7]
	v_cndmask_b32_e64 v2, v173, v2, s[6:7]
	v_pk_mul_f32 v[176:177], v[174:175], v[2:3] op_sel_hi:[1,0]
	v_pk_mul_f32 v[174:175], v[240:241], v[2:3] op_sel_hi:[1,0]
	v_mul_f32_e32 v2, v89, v87
	v_cndmask_b32_e64 v2, v89, v2, s[6:7]
	v_pk_mul_f32 v[184:185], v[90:91], v[2:3] op_sel_hi:[1,0]
	v_pk_mul_f32 v[182:183], v[182:183], v[2:3] op_sel_hi:[1,0]
	s_waitcnt lgkmcnt(0)
	v_mul_f32_e32 v2, v99, v86
	v_mov_b32_e32 v187, v96
	v_cndmask_b32_e64 v2, v99, v2, s[6:7]
	v_pk_mul_f32 v[84:85], v[186:187], v[84:85]
	v_pk_mul_f32 v[188:189], v[188:189], v[2:3] op_sel_hi:[1,0]
	v_pk_mul_f32 v[186:187], v[84:85], v[2:3] op_sel_hi:[1,0]
	v_mul_f32_e32 v2, v98, v99
	v_pk_mul_f32 v[178:179], v[178:179], v[172:173] op_sel_hi:[1,0]
	v_mul_f32_e32 v171, v2, v86
	s_mov_b64 s[8:9], 0

; #define SBAR() __builtin_amdgcn_sched_barrier(0)
; template <int D0, int KS0> __device__ __forceinline__ void pv_one(f32x16& od, int vb, const bf16x8* pa) {
;     const s16x4 l0 = tr_read<v_rd_off(D0, KS0, 0)>(vb), h0 = tr_read<v_rd_off(D0, KS0, 1)>(vb), l1 = tr_read<v_rd_off(D0, KS0 + 1, 0)>(vb), h1 = tr_read<v_rd_off(D0, KS0 + 1, 1)>(vb);
;     asm volatile("s_waitcnt lgkmcnt(0)" ::: "memory"); SBAR();
;     od = __builtin_amdgcn_mfma_f32_32x32x16_bf16(pa[0], PKV(l0, h0), od, 0, 0, 0);
;     od = __builtin_amdgcn_mfma_f32_32x32x16_bf16(pa[1], PKV(l1, h1), od, 0, 0, 0);
; }
; template <int KS0> __device__ __forceinline__ void pv_blk(f32x16* o, int vb, const bf16x8* pa) {
;     pv_one<0, KS0>(o[0], vb, pa); pv_one<1, KS0>(o[1], vb, pa); pv_one<2, KS0>(o[2], vb, pa); pv_one<3, KS0>(o[3], vb, pa);
; }
; __device__ __forceinline__ void pack_p(const f32x16& P, bf16x8& out0, bf16x8& out1) {
;     ...
;     PK4(0, out0); PK4(8, out1);
;     ...
; }
.LBB0_880:
	v_cvt_pk_bf16_f32 v84, v186, v187
	v_cvt_pk_bf16_f32 v85, v188, v189
	v_cvt_pk_bf16_f32 v86, v184, v185
	v_cvt_pk_bf16_f32 v87, v182, v183
	v_cvt_pk_bf16_f32 v88, v178, v179
	v_cvt_pk_bf16_f32 v89, v180, v181
	v_cvt_pk_bf16_f32 v90, v176, v177
	v_cvt_pk_bf16_f32 v91, v174, v175
	s_nop 0
	v_permlane32_swap_b32_e32 v84, v86
	v_permlane32_swap_b32_e32 v85, v87
	v_permlane32_swap_b32_e32 v88, v90
	v_permlane32_swap_b32_e32 v89, v91
	ds_read_b64_tr_b16 v[92:93], v170 offset:0
	ds_read_b64_tr_b16 v[94:95], v170 offset:2048
	ds_read_b64_tr_b16 v[96:97], v170 offset:4096
	ds_read_b64_tr_b16 v[98:99], v170 offset:6144
	ds_read_b64_tr_b16 v[172:173], v170 offset:512
	ds_read_b64_tr_b16 v[174:175], v170 offset:2560
	s_waitcnt lgkmcnt(4)
	v_mfma_f32_32x32x16_bf16 v[52:67], v[84:87], v[92:95], v[52:67]
	ds_read_b64_tr_b16 v[176:177], v170 offset:4608
	ds_read_b64_tr_b16 v[178:179], v170 offset:6656
	s_waitcnt lgkmcnt(4)
	v_mfma_f32_32x32x16_bf16 v[52:67], v[88:91], v[96:99], v[52:67]
	ds_read_b64_tr_b16 v[92:93], v170 offset:1024
	ds_read_b64_tr_b16 v[94:95], v170 offset:3072
	s_waitcnt lgkmcnt(4)
	v_mfma_f32_32x32x16_bf16 v[36:51], v[84:87], v[172:175], v[36:51]
	ds_read_b64_tr_b16 v[96:97], v170 offset:5120
	ds_read_b64_tr_b16 v[98:99], v170 offset:7168
	s_waitcnt lgkmcnt(4)
	v_mfma_f32_32x32x16_bf16 v[36:51], v[88:91], v[176:179], v[36:51]
	ds_read_b64_tr_b16 v[172:173], v170 offset:1536
	ds_read_b64_tr_b16 v[174:175], v170 offset:3584
	s_waitcnt lgkmcnt(4)
	v_mfma_f32_32x32x16_bf16 v[20:35], v[84:87], v[92:95], v[20:35]
	ds_read_b64_tr_b16 v[176:177], v170 offset:5632
	ds_read_b64_tr_b16 v[178:179], v170 offset:7680
	s_waitcnt lgkmcnt(4)
	v_mfma_f32_32x32x16_bf16 v[20:35], v[88:91], v[96:99], v[20:35]
	s_waitcnt lgkmcnt(2)
	v_mfma_f32_32x32x16_bf16 v[4:19], v[84:87], v[172:175], v[4:19]
	s_waitcnt lgkmcnt(0)
	v_mfma_f32_32x32x16_bf16 v[4:19], v[88:91], v[176:179], v[4:19]
	s_andn2_b64 vcc, exec, s[46:47]
	s_cbranch_vccz .LBB0_863
	s_branch .LBB0_864
